# hg<false>: all step-4 fragments read up front into free registers, the 8 MFMAs interleaved with the LF converts and next-chunk load issue
# speedup vs baseline: 1.0063x; 1.0028x over previous
; template <bool FULL, bool STORE = true>
; __device__ __forceinline__ void hg_item(const Prm& P, LAS unsigned char* lds, int item, int wave) {
;     ...
;     f32x16 S[2];
; #pragma unroll
;     for (int i = 0; i < 2; ++i)
; #pragma unroll
;         for (int r = 0; r < 16; ++r) S[i][r] = 0.f;
;     ...
;     HG_LOADS(0);
;     for (int ch = 0; ch < 16; ++ch) {
;         const size_t row0 = (size_t)b * SEQ + seg * 1024 + ch * 64;
;         float ka[8], kc[8], f0[8], f1[8]; float t0 = 0.f, t1 = 0.f;
; #pragma unroll
;         for (int i = 0; i < 8; ++i) { f0[i] = __expf(c0[i]); f1[i] = __expf(c1[i]); ka[i] = 1.0f - f0[i]; kc[i] = 1.0f - f1[i]; t0 += c0[i]; t1 += c1[i]; }
.LBB0_700:
	s_lshl_b32 s36, s62, 1
	s_and_b32 s26, s60, 0x1c00
	s_and_b32 s67, s36, 0x700
	s_ashr_i32 s36, s65, 6
	s_lshl_b32 s66, s65, 10
	s_add_i32 s26, s33, s26
	s_ashr_i32 s37, s36, 31
	s_and_b32 s66, s66, 0x1c00
	s_lshl_b64 s[34:35], s[26:27], 11
	s_lshl_b64 s[38:39], s[36:37], 13
	s_add_i32 s66, s66, s33
	s_add_u32 s72, s38, s66
	v_mbcnt_lo_u32_b32 v36, -1, 0
	v_mbcnt_hi_u32_b32 v36, -1, v36
	s_addc_u32 s73, s39, 0
	v_lshlrev_b32_e32 v34, 1, v36
	s_lshl_b32 s66, s65, 4
	s_and_b32 s74, s66, 0x380
	s_mov_b32 s75, s27
	v_ashrrev_i32_e32 v35, 31, v34
	v_lshl_add_u64 v[38:39], v[34:35], 0, s[74:75]
	s_lshl_b64 s[72:73], s[72:73], 10
	v_lshl_add_u64 v[0:1], v[38:39], 0, s[72:73]
	v_lshlrev_b64 v[0:1], 1, v[0:1]
	v_lshl_add_u64 v[2:3], s[70:71], 0, v[0:1]
	s_mov_b64 s[72:73], 0x1000
	global_load_dword v16, v[2:3], off
	global_load_dword v17, v[2:3], off offset:2048
	v_lshl_add_u64 v[2:3], v[0:1], 0, s[72:73]
	v_lshl_add_u64 v[4:5], s[70:71], 0, v[2:3]
	s_mov_b64 s[72:73], 0x1800
	global_load_dword v18, v[4:5], off
	v_lshl_add_u64 v[4:5], v[0:1], 0, s[72:73]
	v_lshl_add_u64 v[6:7], s[70:71], 0, v[4:5]
	s_mov_b64 s[72:73], 0x2000
	global_load_dword v19, v[6:7], off
	v_lshl_add_u64 v[6:7], v[0:1], 0, s[72:73]
	v_lshl_add_u64 v[8:9], s[70:71], 0, v[6:7]
	s_mov_b64 s[72:73], 0x2800
	global_load_dword v20, v[8:9], off
	v_lshl_add_u64 v[8:9], v[0:1], 0, s[72:73]
	v_lshl_add_u64 v[10:11], s[70:71], 0, v[8:9]
	s_mov_b64 s[72:73], 0x3000
	global_load_dword v21, v[10:11], off
	v_lshl_add_u64 v[10:11], v[0:1], 0, s[72:73]
	v_lshl_add_u64 v[12:13], s[70:71], 0, v[10:11]
	s_mov_b64 s[72:73], 0x3800
	global_load_dword v22, v[12:13], off
	v_lshl_add_u64 v[12:13], v[0:1], 0, s[72:73]
	v_lshl_add_u64 v[14:15], s[70:71], 0, v[12:13]
	v_lshl_add_u64 v[0:1], s[24:25], 0, v[0:1]
	global_load_dword v14, v[14:15], off
	s_nop 0
	global_load_dword v37, v[0:1], off
	global_load_dword v65, v[0:1], off offset:2048
	v_lshl_add_u64 v[0:1], s[24:25], 0, v[2:3]
	v_lshl_add_u64 v[2:3], s[24:25], 0, v[4:5]
	v_lshl_add_u64 v[4:5], s[24:25], 0, v[6:7]
	v_lshl_add_u64 v[6:7], s[24:25], 0, v[8:9]
	v_lshl_add_u64 v[8:9], s[24:25], 0, v[10:11]
	v_lshl_add_u64 v[10:11], s[24:25], 0, v[12:13]
	global_load_dword v68, v[0:1], off
	global_load_dword v69, v[2:3], off
	global_load_dword v70, v[4:5], off
	global_load_dword v71, v[6:7], off
	global_load_dword v72, v[8:9], off
	global_load_dword v75, v[10:11], off
	s_add_u32 s38, s38, s26
	s_addc_u32 s39, s39, 0
	s_lshl_b64 s[38:39], s[38:39], 10
	s_add_u32 s26, s38, 0x10000
	v_and_b32_e32 v0, 31, v36
	s_movk_i32 s72, 0x120
	v_ashrrev_i32_e32 v1, 1, v36
	s_addc_u32 s38, s39, 0
	s_lshl_b64 s[36:37], s[36:37], 24
	v_mul_lo_u32 v66, v36, s72
	v_and_b32_e32 v67, -16, v1
	v_or_b32_e32 v1, s50, v0
	s_movk_i32 s72, 0x90
	s_add_u32 s34, s36, s34
	v_or_b32_e32 v0, s51, v0
	v_mul_lo_u32 v1, v1, s72
	s_addc_u32 s35, s37, s35
	s_or_b32 s34, s34, s67
	v_mul_u32_u24_e32 v3, 0x90, v0
	v_add_u32_e32 v4, 0, v1
	v_mov_b32_e32 v0, s34
	v_mov_b32_e32 v1, s35
	v_add_u32_e32 v2, s64, v67
	v_lshl_add_u64 v[0:1], v[34:35], 1, v[0:1]
	v_mov_b32_e32 v33, v32
	v_lshlrev_b32_e32 v64, 3, v36
	v_lshl_add_u64 v[42:43], s[28:29], 0, v[0:1]
	v_lshl_add_u64 v[44:45], s[30:31], 0, v[0:1]
	s_mov_b64 s[34:35], 0
	v_add_u32_e32 v73, v4, v67
	v_add_u32_e32 v74, v2, v3
	v_mov_b64_e32 v[40:41], v[32:33]
	v_mov_b32_e32 v23, v32
	v_mov_b32_e32 v24, v32
	v_mov_b32_e32 v25, v32
	v_mov_b32_e32 v26, v32
	v_mov_b32_e32 v27, v32
	v_mov_b32_e32 v28, v32
	v_mov_b32_e32 v29, v32
	v_mov_b32_e32 v30, v32
	v_mov_b32_e32 v31, v32
	v_mov_b32_e32 v0, 0
	v_mov_b32_e32 v1, v32
	v_mov_b32_e32 v2, v32
	v_mov_b32_e32 v3, v32
	v_mov_b32_e32 v4, v32
	s_waitcnt vmcnt(0)
	v_cvt_f32_f16_e32 v46, v16
	v_cvt_f32_f16_sdwa v47, v16 dst_sel:DWORD dst_unused:UNUSED_PAD src0_sel:WORD_1
	v_cvt_f32_f16_e32 v48, v17
	v_cvt_f32_f16_sdwa v49, v17 dst_sel:DWORD dst_unused:UNUSED_PAD src0_sel:WORD_1
	v_mov_b32_e32 v16, 0
	v_cvt_f32_f16_e32 v50, v18
	v_cvt_f32_f16_sdwa v51, v18 dst_sel:DWORD dst_unused:UNUSED_PAD src0_sel:WORD_1
	v_mov_b32_e32 v17, v32
	v_mov_b32_e32 v18, v32
	v_cvt_f32_f16_e32 v52, v19
	v_cvt_f32_f16_sdwa v53, v19 dst_sel:DWORD dst_unused:UNUSED_PAD src0_sel:WORD_1
	v_mov_b32_e32 v19, v32
	v_mov_b32_e32 v5, v32
	v_cvt_f32_f16_e32 v54, v20
	v_cvt_f32_f16_sdwa v55, v20 dst_sel:DWORD dst_unused:UNUSED_PAD src0_sel:WORD_1
	v_mov_b32_e32 v20, v32
	v_mov_b32_e32 v6, v32
	v_cvt_f32_f16_e32 v56, v21
	v_cvt_f32_f16_sdwa v57, v21 dst_sel:DWORD dst_unused:UNUSED_PAD src0_sel:WORD_1
	v_mov_b32_e32 v21, v32
	v_mov_b32_e32 v7, v32
	v_cvt_f32_f16_e32 v58, v22
	v_cvt_f32_f16_sdwa v59, v22 dst_sel:DWORD dst_unused:UNUSED_PAD src0_sel:WORD_1
	v_mov_b32_e32 v22, v32
	v_mov_b32_e32 v8, v32
	v_cvt_f32_f16_e32 v60, v14
	v_cvt_f32_f16_sdwa v61, v14 dst_sel:DWORD dst_unused:UNUSED_PAD src0_sel:WORD_1
	v_mov_b32_e32 v9, v32
	v_mov_b32_e32 v10, v32
	v_mov_b32_e32 v11, v32
	v_mov_b32_e32 v12, v32
	v_mov_b32_e32 v13, v32
	v_mov_b32_e32 v14, v32
	v_mov_b32_e32 v15, v32
	v_mov_b32_e32 v116, 0
	v_mov_b32_e32 v117, 0
	v_mov_b32_e32 v118, 0
	v_mov_b32_e32 v119, 0
	v_mov_b32_e32 v120, 0
	v_mov_b32_e32 v121, 0
	v_mov_b32_e32 v122, 0
	v_mov_b32_e32 v123, 0
	v_mov_b32_e32 v132, 0
	v_mov_b32_e32 v133, 0
	v_mov_b32_e32 v134, 0
	v_mov_b32_e32 v135, 0
	v_mov_b32_e32 v136, 0
	v_mov_b32_e32 v137, 0
	v_mov_b32_e32 v138, 0
	v_mov_b32_e32 v139, 0
	v_mov_b32_e32 v148, 0
	v_mov_b32_e32 v149, 0
	v_mov_b32_e32 v150, 0
	v_mov_b32_e32 v151, 0
	v_mov_b32_e32 v152, 0
	v_mov_b32_e32 v153, 0
	v_mov_b32_e32 v154, 0
	v_mov_b32_e32 v155, 0
	s_branch .LBB0_702
; #define LAS __attribute__((address_space(3)))
; template <bool FULL, bool STORE = true>
; __device__ __forceinline__ void hg_item(const Prm& P, LAS unsigned char* lds, int item, int wave) {
;     ...
;     HG_LOADS(0);
;     ...
; #pragma unroll
;         for (int g4 = 0; g4 < 4; ++g4) { const f32x4 d = *(const LAS f32x4*)(lds + HL_DC + (kb * 32 + 8 * g4 + 4 * lh) * 4);
; #pragma unroll
;             for (int i = 0; i < 2; ++i)
; #pragma unroll
;                 for (int j = 0; j < 4; ++j) S[i][4 * g4 + j] *= d[j]; }
; #pragma unroll
;         for (int ks = 0; ks < 4; ++ks) { const bf16x8 a = *(const LAS bf16x8*)(lds + HL_KDT + (kb * 32 + l31) * 144 + ks * 32 + lh * 16);
; #pragma unroll
;             for (int i = 0; i < 2; ++i) { const bf16x8 bb = *(const LAS bf16x8*)(lds + HL_IVT + ((vb0 + i) * 32 + l31) * 144 + ks * 32 + lh * 16); S[i] = __builtin_amdgcn_mfma_f32_32x32x16_bf16(a, bb, S[i], 0, 0, 0); } }
.LBB0_701:
	v_add_u32_e32 v33, s48, v67
	s_waitcnt lgkmcnt(0)
	s_barrier
	ds_read_b128 v[156:159], v33
	ds_read_b128 v[160:163], v33 offset:32
	ds_read_b128 v[164:167], v33 offset:64
	ds_read_b128 v[168:171], v33 offset:96
	ds_read_b128 v[108:111], v73 offset:52224
	ds_read_b128 v[124:127], v74
	ds_read_b128 v[140:143], v74 offset:4608
	ds_read_b128 v[112:115], v73 offset:52256
	ds_read_b128 v[128:131], v74 offset:32
	ds_read_b128 v[144:147], v74 offset:4640
	ds_read_b128 v[116:119], v73 offset:52288
	ds_read_b128 v[132:135], v74 offset:64
	ds_read_b128 v[148:151], v74 offset:4672
	ds_read_b128 v[120:123], v73 offset:52320
	ds_read_b128 v[136:139], v74 offset:96
	ds_read_b128 v[152:155], v74 offset:4704
	s_add_u32 s34, s34, 0x20000
	s_addc_u32 s35, s35, 0
	s_add_u32 s26, s26, 0x10000
	s_addc_u32 s38, s38, 0
	s_cmp_eq_u32 s34, 0x200000
	s_waitcnt lgkmcnt(15)
	v_pk_mul_f32 v[16:17], v[16:17], v[156:157]
	v_pk_mul_f32 v[18:19], v[18:19], v[158:159]
	v_pk_mul_f32 v[0:1], v[0:1], v[156:157]
	v_pk_mul_f32 v[2:3], v[2:3], v[158:159]
	s_waitcnt lgkmcnt(14)
	v_pk_mul_f32 v[20:21], v[20:21], v[160:161]
	v_pk_mul_f32 v[22:23], v[22:23], v[162:163]
	v_pk_mul_f32 v[4:5], v[4:5], v[160:161]
	v_pk_mul_f32 v[6:7], v[6:7], v[162:163]
	s_waitcnt lgkmcnt(13)
	v_pk_mul_f32 v[24:25], v[24:25], v[164:165]
	v_pk_mul_f32 v[26:27], v[26:27], v[166:167]
	v_pk_mul_f32 v[8:9], v[8:9], v[164:165]
	v_pk_mul_f32 v[10:11], v[10:11], v[166:167]
	s_waitcnt lgkmcnt(12)
	v_pk_mul_f32 v[28:29], v[28:29], v[168:169]
	v_pk_mul_f32 v[30:31], v[30:31], v[170:171]
	v_pk_mul_f32 v[12:13], v[12:13], v[168:169]
	v_pk_mul_f32 v[14:15], v[14:15], v[170:171]
	s_waitcnt lgkmcnt(0)
	s_cbranch_scc1 .Lmy_hgf_last
	v_mfma_f32_32x32x16_bf16 v[16:31], v[108:111], v[124:127], v[16:31]
	s_waitcnt vmcnt(0)
	v_cvt_f32_f16_e32 v46, v240
	v_cvt_f32_f16_sdwa v47, v240 dst_sel:DWORD dst_unused:UNUSED_PAD src0_sel:WORD_1
	v_cvt_f32_f16_e32 v48, v241
	v_cvt_f32_f16_sdwa v49, v241 dst_sel:DWORD dst_unused:UNUSED_PAD src0_sel:WORD_1
	v_cvt_f32_f16_e32 v50, v242
	v_cvt_f32_f16_sdwa v51, v242 dst_sel:DWORD dst_unused:UNUSED_PAD src0_sel:WORD_1
	v_mfma_f32_32x32x16_bf16 v[0:15], v[108:111], v[140:143], v[0:15]
	v_cvt_f32_f16_e32 v52, v243
	v_cvt_f32_f16_sdwa v53, v243 dst_sel:DWORD dst_unused:UNUSED_PAD src0_sel:WORD_1
	v_cvt_f32_f16_e32 v54, v244
	v_cvt_f32_f16_sdwa v55, v244 dst_sel:DWORD dst_unused:UNUSED_PAD src0_sel:WORD_1
	v_cvt_f32_f16_e32 v56, v245
	v_cvt_f32_f16_sdwa v57, v245 dst_sel:DWORD dst_unused:UNUSED_PAD src0_sel:WORD_1
	v_mfma_f32_32x32x16_bf16 v[16:31], v[112:115], v[128:131], v[16:31]
	v_cvt_f32_f16_e32 v58, v246
	v_cvt_f32_f16_sdwa v59, v246 dst_sel:DWORD dst_unused:UNUSED_PAD src0_sel:WORD_1
	v_cvt_f32_f16_e32 v60, v247
	v_cvt_f32_f16_sdwa v61, v247 dst_sel:DWORD dst_unused:UNUSED_PAD src0_sel:WORD_1
	v_mov_b32_e32 v37, v232
	v_mov_b32_e32 v65, v233
	v_mfma_f32_32x32x16_bf16 v[0:15], v[112:115], v[144:147], v[0:15]
	v_mov_b32_e32 v68, v234
	v_mov_b32_e32 v69, v235
	v_mov_b32_e32 v70, v236
	v_mov_b32_e32 v71, v237
	v_mov_b32_e32 v72, v238
	v_mov_b32_e32 v75, v239
	s_nop 0
.LBB0_702:
	s_cmp_eq_u32 s34, 0x1e0000
	s_cbranch_scc1 .Lmy_hgf_skipl
	v_lshl_add_u64 v[224:225], v[42:43], 0, s[34:35]
	global_load_dword v240, v[224:225], off
	v_lshl_add_u64 v[224:225], v[44:45], 0, s[34:35]
	s_or_b32 s36, s26, 0x400
	s_mov_b32 s37, s38
	global_load_dword v232, v[224:225], off
	v_lshl_add_u64 v[224:225], s[36:37], 0, v[38:39]
	v_lshlrev_b64 v[224:225], 1, v[224:225]
	v_lshl_add_u64 v[226:227], s[70:71], 0, v[224:225]
	v_lshl_add_u64 v[224:225], s[24:25], 0, v[224:225]
	v_mfma_f32_32x32x16_bf16 v[16:31], v[116:119], v[132:135], v[16:31]
	s_or_b32 s36, s26, 0x800
	global_load_dword v233, v[224:225], off
	v_lshl_add_u64 v[224:225], s[36:37], 0, v[38:39]
	v_lshlrev_b64 v[224:225], 1, v[224:225]
	global_load_dword v241, v[226:227], off
	v_lshl_add_u64 v[226:227], s[70:71], 0, v[224:225]
	v_lshl_add_u64 v[224:225], s[24:25], 0, v[224:225]
	s_or_b32 s36, s26, 0xc00
	global_load_dword v234, v[224:225], off
	v_lshl_add_u64 v[224:225], s[36:37], 0, v[38:39]
	v_lshlrev_b64 v[224:225], 1, v[224:225]
	v_mfma_f32_32x32x16_bf16 v[0:15], v[116:119], v[148:151], v[0:15]
	global_load_dword v242, v[226:227], off
	v_lshl_add_u64 v[226:227], s[70:71], 0, v[224:225]
	v_lshl_add_u64 v[224:225], s[24:25], 0, v[224:225]
	s_or_b32 s36, s26, 0x1000
	global_load_dword v235, v[224:225], off
	v_lshl_add_u64 v[224:225], s[36:37], 0, v[38:39]
	v_lshlrev_b64 v[224:225], 1, v[224:225]
	global_load_dword v243, v[226:227], off
	v_lshl_add_u64 v[226:227], s[70:71], 0, v[224:225]
	v_lshl_add_u64 v[224:225], s[24:25], 0, v[224:225]
	s_or_b32 s36, s26, 0x1400
	v_mfma_f32_32x32x16_bf16 v[16:31], v[120:123], v[136:139], v[16:31]
	global_load_dword v236, v[224:225], off
	v_lshl_add_u64 v[224:225], s[36:37], 0, v[38:39]
	v_lshlrev_b64 v[224:225], 1, v[224:225]
	global_load_dword v244, v[226:227], off
	v_lshl_add_u64 v[226:227], s[70:71], 0, v[224:225]
	s_or_b32 s36, s26, 0x1800
	global_load_dword v245, v[226:227], off
	v_lshl_add_u64 v[226:227], s[36:37], 0, v[38:39]
	v_lshlrev_b64 v[226:227], 1, v[226:227]
	v_lshl_add_u64 v[228:229], s[70:71], 0, v[226:227]
	s_or_b32 s36, s26, 0x1c00
	v_mfma_f32_32x32x16_bf16 v[0:15], v[120:123], v[152:155], v[0:15]
	global_load_dword v246, v[228:229], off
	v_lshl_add_u64 v[228:229], s[36:37], 0, v[38:39]
	v_lshlrev_b64 v[228:229], 1, v[228:229]
	v_lshl_add_u64 v[230:231], s[70:71], 0, v[228:229]
	v_lshl_add_u64 v[224:225], s[24:25], 0, v[224:225]
	global_load_dword v247, v[230:231], off
	global_load_dword v237, v[224:225], off
	v_lshl_add_u64 v[224:225], s[24:25], 0, v[226:227]
	global_load_dword v238, v[224:225], off
	v_lshl_add_u64 v[224:225], s[24:25], 0, v[228:229]
	global_load_dword v239, v[224:225], off

; #define LAS __attribute__((address_space(3)))
; template <bool FULL, bool STORE = true>
; __device__ __forceinline__ void hg_item(const Prm& P, LAS unsigned char* lds, int item, int wave) {
;     ...
;         for (int ks = 0; ks < 4; ++ks) { const bf16x8 a = *(const LAS bf16x8*)(lds + HL_KDT + (kb * 32 + l31) * 144 + ks * 32 + lh * 16);
; #pragma unroll
;             for (int i = 0; i < 2; ++i) { const bf16x8 bb = *(const LAS bf16x8*)(lds + HL_IVT + ((vb0 + i) * 32 + l31) * 144 + ks * 32 + lh * 16); S[i] = __builtin_amdgcn_mfma_f32_32x32x16_bf16(a, bb, S[i], 0, 0, 0); } }
.Lmy_hgf_skipl:
	v_mfma_f32_32x32x16_bf16 v[16:31], v[116:119], v[132:135], v[16:31]
	v_mfma_f32_32x32x16_bf16 v[0:15], v[116:119], v[148:151], v[0:15]
	v_mfma_f32_32x32x16_bf16 v[16:31], v[120:123], v[136:139], v[16:31]
	v_mfma_f32_32x32x16_bf16 v[0:15], v[120:123], v[152:155], v[0:15]
	s_branch .Lhgf_noload
.Lmy_hgf_last:
	v_mfma_f32_32x32x16_bf16 v[16:31], v[108:111], v[124:127], v[16:31]
	v_mfma_f32_32x32x16_bf16 v[0:15], v[108:111], v[140:143], v[0:15]
	v_mfma_f32_32x32x16_bf16 v[16:31], v[112:115], v[128:131], v[16:31]
	v_mfma_f32_32x32x16_bf16 v[0:15], v[112:115], v[144:147], v[0:15]
	v_mfma_f32_32x32x16_bf16 v[16:31], v[116:119], v[132:135], v[16:31]
	v_mfma_f32_32x32x16_bf16 v[0:15], v[116:119], v[148:151], v[0:15]
	v_mfma_f32_32x32x16_bf16 v[16:31], v[120:123], v[136:139], v[16:31]
	v_mfma_f32_32x32x16_bf16 v[0:15], v[120:123], v[152:155], v[0:15]
	s_nop 15
